# bundle: attention loop edits, V DMA ahead of barrier, loop bookkeeping ahead of barrier, retention-output decay and GroupNorm-weight loads issued early
# baseline (speedup 1.0000x reference)
;   #define RESC() do{ if(resc){ asm volatile("s_waitcnt lgkmcnt(0)":::"memory"); \
;       _Pragma("unroll") for(int d_=0;d_<2;++d_) _Pragma("unroll") for(int r=0;r<16;++r)o[d_][r]*=wsf[crow(r,hi)]; } }while(0)
;   #define ROT() do{sl_prev=sl_cur;sl_cur=sl_next;sl_next=(sl_next==(NSLOT-1)*SLOTB)?0:sl_next+SLOTB;}while(0)
;   #define WAIT_STEADY() WAIT_BAR(3)
;   #define WAIT_STEADY() WAIT_BAR(2)
; template<int THRL,bool NOMAX> __device__ __forceinline__ void attn_unit(int b,int h,int qb,int t0,const bf16*Q,const bf16*__restrict__ KV,const bf16*__restrict__ GA,bf16*O,char*shm){
;     ...
;   for(;t+5<NT;t+=2){
;     STEP(pB0,pB1,pA0,pA1,t,true,true,true);     WAIT_STEADY(); RESC(); ROT();
.LBB0_479:
	v_add_u32_e32 v179, s16, v2
	ds_read_b64_tr_b16 v[198:199], v179 offset:24576
	ds_read_b64_tr_b16 v[200:201], v179 offset:25088
	v_add_f32_e32 v88, v68, v69
	v_add_f32_e32 v88, v70, v88
	v_add_f32_e32 v88, v71, v88
	v_add_f32_e32 v88, v72, v88
	v_add_f32_e32 v88, v73, v88
	v_cvt_pk_bf16_f32 v160, v68, v69
	v_cvt_pk_bf16_f32 v161, v70, v71
	v_mfma_f32_32x32x16_bf16 v[100:115], v[84:87], v[152:155], v[36:51]
	ds_read_b64_tr_b16 v[202:203], v179 offset:28672
	ds_read_b64_tr_b16 v[204:205], v179 offset:29184
	v_add_f32_e32 v68, v74, v88
	v_mfma_f32_32x32x16_bf16 v[84:99], v[168:171], v[152:155], v[36:51]
	v_add_f32_e32 v68, v75, v68
	v_add_f32_e32 v68, v76, v68
	v_add_f32_e32 v140, v77, v68
	v_cvt_pk_bf16_f32 v162, v72, v73
	v_cvt_pk_bf16_f32 v163, v74, v75
	ds_read_b64_tr_b16 v[68:69], v179 offset:25600
	ds_read_b64_tr_b16 v[70:71], v179 offset:26112
	v_add_f32_e32 v72, v78, v140
	v_add_f32_e32 v72, v79, v72
	v_add_f32_e32 v72, v80, v72
	v_add_f32_e32 v140, v81, v72
	v_cvt_pk_bf16_f32 v156, v76, v77
	v_cvt_pk_bf16_f32 v157, v78, v79
	v_mfma_f32_32x32x16_bf16 v[100:115], v[172:175], v[144:147], v[100:115]
	ds_read_b64_tr_b16 v[72:73], v179 offset:29696
	ds_read_b64_tr_b16 v[74:75], v179 offset:30208
	v_mfma_f32_32x32x16_bf16 v[84:99], v[164:167], v[144:147], v[84:99]
	v_add_f32_e32 v76, v82, v140
	v_add_f32_e32 v76, v83, v76
	v_add_f32_e32 v76, v52, v76
	v_add_f32_e32 v140, v53, v76
	v_cvt_pk_bf16_f32 v158, v80, v81
	v_cvt_pk_bf16_f32 v159, v82, v83
	ds_read_b64_tr_b16 v[76:77], v179 offset:26624
	ds_read_b64_tr_b16 v[78:79], v179 offset:27136
	v_add_f32_e32 v80, v54, v140
	v_add_f32_e32 v80, v55, v80
	v_add_f32_e32 v80, v56, v80
	v_add_f32_e32 v80, v57, v80
	v_cvt_pk_bf16_f32 v148, v52, v53
	v_cvt_pk_bf16_f32 v149, v54, v55
	v_mfma_f32_32x32x16_bf16 v[100:115], v[128:131], v[136:139], v[100:115]
	ds_read_b64_tr_b16 v[52:53], v179 offset:30720
	ds_read_b64_tr_b16 v[54:55], v179 offset:31232
	v_mfma_f32_32x32x16_bf16 v[84:99], v[124:127], v[136:139], v[84:99]
	v_add_f32_e32 v80, v58, v80
	v_add_f32_e32 v80, v59, v80
	v_add_f32_e32 v80, v60, v80
	v_add_f32_e32 v80, v61, v80
	v_cvt_pk_bf16_f32 v150, v56, v57
	v_cvt_pk_bf16_f32 v151, v58, v59
	ds_read_b64_tr_b16 v[56:57], v179 offset:27648
	ds_read_b64_tr_b16 v[58:59], v179 offset:28160
	v_add_f32_e32 v80, v62, v80
	v_add_f32_e32 v80, v63, v80
	v_add_f32_e32 v80, v64, v80
	v_add_f32_e32 v80, v65, v80
	v_cvt_pk_bf16_f32 v140, v60, v61
	v_cvt_pk_bf16_f32 v141, v62, v63
	v_mfma_f32_32x32x16_bf16 v[100:115], v[120:123], v[132:135], v[100:115]
	ds_read_b64_tr_b16 v[60:61], v179 offset:31744
	ds_read_b64_tr_b16 v[62:63], v179 offset:32256
	v_mfma_f32_32x32x16_bf16 v[84:99], v[116:119], v[132:135], v[84:99]
	v_add_f32_e32 v80, v66, v80
	v_add_f32_e32 v80, v67, v80
	v_add_f32_e32 v179, 0, v80
	v_cvt_pk_bf16_f32 v142, v64, v65
	v_cvt_pk_bf16_f32 v143, v66, v67
	s_add_i32 s16, s21, 0x4000
	s_and_b32 s16, s16, 0xfc000
	s_lshl_b32 s16, s16, 1
	v_lshl_add_u64 v[218:219], v[182:183], 0, s[16:17]
	s_add_i32 m0, s22, s9
	s_nop 0
	global_load_lds_dwordx4 v[218:219], off
	s_waitcnt lgkmcnt(4)
	v_mfma_f32_32x32x16_bf16 v[4:19], v[160:163], v[198:201], v[4:19]
	v_exp_f32_e32 v100, v100
	v_exp_f32_e32 v101, v101
	v_exp_f32_e32 v102, v102
	v_exp_f32_e32 v103, v103
	v_mfma_f32_32x32x16_bf16 v[20:35], v[160:163], v[202:205], v[20:35]
	v_exp_f32_e32 v104, v104
	v_exp_f32_e32 v105, v105
	v_exp_f32_e32 v106, v106
	v_exp_f32_e32 v107, v107
	v_add_u32_e32 v80, s15, v189
	ds_read_b128 v[64:67], v80
	ds_read_b128 v[120:123], v80 offset:512
	v_mfma_f32_32x32x16_bf16 v[4:19], v[156:159], v[68:71], v[4:19]
	v_exp_f32_e32 v108, v108
	v_exp_f32_e32 v109, v109
	v_exp_f32_e32 v110, v110
	v_exp_f32_e32 v111, v111
	ds_read_b128 v[124:127], v80 offset:2048
	ds_read_b128 v[128:131], v80 offset:2560
	v_mfma_f32_32x32x16_bf16 v[20:35], v[156:159], v[72:75], v[20:35]
	v_exp_f32_e32 v112, v112
	v_exp_f32_e32 v113, v113
	v_exp_f32_e32 v114, v114
	v_exp_f32_e32 v115, v115
	ds_read_b128 v[164:167], v80 offset:4096
	ds_read_b128 v[168:171], v80 offset:4608
	v_mfma_f32_32x32x16_bf16 v[4:19], v[148:151], v[76:79], v[4:19]
	v_exp_f32_e32 v84, v84
	v_exp_f32_e32 v85, v85
	v_exp_f32_e32 v86, v86
	v_exp_f32_e32 v87, v87
	ds_read_b128 v[172:175], v80 offset:6144
	ds_read_b128 v[116:119], v80 offset:6656
	v_mfma_f32_32x32x16_bf16 v[20:35], v[148:151], v[52:55], v[20:35]
	v_exp_f32_e32 v88, v88
	v_exp_f32_e32 v89, v89
	v_exp_f32_e32 v90, v90
	v_exp_f32_e32 v91, v91
	s_waitcnt lgkmcnt(8)
	v_mfma_f32_32x32x16_bf16 v[4:19], v[140:143], v[56:59], v[4:19]
	v_exp_f32_e32 v92, v92
	v_exp_f32_e32 v93, v93
	v_exp_f32_e32 v94, v94
	v_exp_f32_e32 v95, v95
	v_mfma_f32_32x32x16_bf16 v[20:35], v[140:143], v[60:63], v[20:35]
	v_exp_f32_e32 v96, v96
	v_exp_f32_e32 v97, v97
	v_exp_f32_e32 v98, v98
	v_exp_f32_e32 v99, v99
	s_add_i32 s16, s20, 0xffff4000
	s_and_b32 s16, s16, 0xfc000
	s_lshl_b32 s16, s16, 1
	v_lshl_add_u64 v[218:219], v[180:181], 0, s[16:17]
	s_add_i32 m0, s15, s8
	s_nop 0
	global_load_lds_dwordx4 v[218:219], off
	s_add_i32 s16, s15, 0x2000
	s_cmpk_lg_i32 s15, 0x4000
	s_cselect_b32 s23, s16, 0
	v_add_u32_e32 v190, s22, v2
	s_waitcnt vmcnt(2) lgkmcnt(0)
	s_barrier
;   #define RESC() do{ if(resc){ asm volatile("s_waitcnt lgkmcnt(0)":::"memory"); \
;       _Pragma("unroll") for(int d_=0;d_<2;++d_) _Pragma("unroll") for(int r=0;r<16;++r)o[d_][r]*=wsf[crow(r,hi)]; } }while(0)
;   #define ROT() do{sl_prev=sl_cur;sl_cur=sl_next;sl_next=(sl_next==(NSLOT-1)*SLOTB)?0:sl_next+SLOTB;}while(0)
;   #define WAIT_STEADY() WAIT_BAR(3)
;   #define WAIT_STEADY() WAIT_BAR(2)
; template<int THRL,bool NOMAX> __device__ __forceinline__ void attn_unit(int b,int h,int qb,int t0,const bf16*Q,const bf16*__restrict__ KV,const bf16*__restrict__ GA,bf16*O,char*shm){
;     ...
;   int t=1;
;     ...
;   for(;t+5<NT;t+=2){
;     STEP(pB0,pB1,pA0,pA1,t,true,true,true);     WAIT_STEADY(); RESC(); ROT();
;     STEP(pA0,pA1,pB0,pB1,t+1,true,true,true);   WAIT_STEADY(); RESC(); ROT();
;   }
	ds_read_b64_tr_b16 v[198:199], v190 offset:24576
	ds_read_b64_tr_b16 v[200:201], v190 offset:25088
	v_mfma_f32_32x32x16_bf16 v[68:83], v[64:67], v[152:155], v[36:51]
	v_add_f32_e32 v52, v100, v101
	v_add_f32_e32 v52, v102, v52
	v_add_f32_e32 v52, v103, v52
	v_add_f32_e32 v52, v104, v52
	v_add_f32_e32 v52, v105, v52
	v_cvt_pk_bf16_f32 v160, v100, v101
	v_cvt_pk_bf16_f32 v161, v102, v103
	ds_read_b64_tr_b16 v[202:203], v190 offset:28672
	ds_read_b64_tr_b16 v[204:205], v190 offset:29184
	v_add_f32_e32 v52, v106, v52
	v_add_f32_e32 v52, v107, v52
	v_add_f32_e32 v52, v108, v52
	v_add_f32_e32 v140, v109, v52
	v_mfma_f32_32x32x16_bf16 v[52:67], v[120:123], v[152:155], v[36:51]
	v_cvt_pk_bf16_f32 v162, v104, v105
	v_cvt_pk_bf16_f32 v163, v106, v107
	ds_read_b64_tr_b16 v[100:101], v190 offset:25600
	ds_read_b64_tr_b16 v[102:103], v190 offset:26112
	v_mfma_f32_32x32x16_bf16 v[68:83], v[124:127], v[144:147], v[68:83]
	v_add_f32_e32 v104, v110, v140
	v_add_f32_e32 v104, v111, v104
	v_add_f32_e32 v104, v112, v104
	v_add_f32_e32 v120, v113, v104
	v_cvt_pk_bf16_f32 v156, v108, v109
	v_cvt_pk_bf16_f32 v157, v110, v111
	ds_read_b64_tr_b16 v[104:105], v190 offset:29696
	ds_read_b64_tr_b16 v[106:107], v190 offset:30208
	v_mfma_f32_32x32x16_bf16 v[52:67], v[128:131], v[144:147], v[52:67]
	v_add_f32_e32 v108, v114, v120
	v_add_f32_e32 v108, v115, v108
	v_add_f32_e32 v108, v84, v108
	v_add_f32_e32 v120, v85, v108
	v_cvt_pk_bf16_f32 v158, v112, v113
	v_cvt_pk_bf16_f32 v159, v114, v115
	ds_read_b64_tr_b16 v[108:109], v190 offset:26624
	ds_read_b64_tr_b16 v[110:111], v190 offset:27136
	v_mfma_f32_32x32x16_bf16 v[68:83], v[164:167], v[136:139], v[68:83]
	v_add_f32_e32 v112, v86, v120
	v_add_f32_e32 v112, v87, v112
	v_add_f32_e32 v112, v88, v112
	v_add_f32_e32 v120, v89, v112
	v_cvt_pk_bf16_f32 v148, v84, v85
	v_cvt_pk_bf16_f32 v149, v86, v87
	ds_read_b64_tr_b16 v[112:113], v190 offset:30720
	ds_read_b64_tr_b16 v[114:115], v190 offset:31232
	v_mfma_f32_32x32x16_bf16 v[52:67], v[168:171], v[136:139], v[52:67]
	v_add_f32_e32 v84, v90, v120
	v_add_f32_e32 v84, v91, v84
	v_add_f32_e32 v84, v92, v84
	v_add_f32_e32 v84, v93, v84
	v_cvt_pk_bf16_f32 v150, v88, v89
	v_cvt_pk_bf16_f32 v151, v90, v91
	ds_read_b64_tr_b16 v[88:89], v190 offset:27648
	ds_read_b64_tr_b16 v[90:91], v190 offset:28160
	v_mfma_f32_32x32x16_bf16 v[68:83], v[172:175], v[132:135], v[68:83]
	v_add_f32_e32 v84, v94, v84
	v_add_f32_e32 v84, v95, v84
	v_add_f32_e32 v84, v96, v84
	v_add_f32_e32 v84, v97, v84
	v_cvt_pk_bf16_f32 v140, v92, v93
	v_cvt_pk_bf16_f32 v141, v94, v95
	ds_read_b64_tr_b16 v[92:93], v190 offset:31744
	ds_read_b64_tr_b16 v[94:95], v190 offset:32256
	v_mfma_f32_32x32x16_bf16 v[52:67], v[116:119], v[132:135], v[52:67]
	v_add_f32_e32 v84, v98, v84
	v_add_f32_e32 v84, v99, v84
	v_add_f32_e32 v190, 0, v84
	v_cvt_pk_bf16_f32 v142, v96, v97
	v_cvt_pk_bf16_f32 v143, v98, v99
	s_and_b32 s16, s20, 0xfc000
	s_lshl_b32 s16, s16, 1
	v_lshl_add_u64 v[218:219], v[182:183], 0, s[16:17]
	s_add_i32 m0, s15, s9
	s_nop 0
	global_load_lds_dwordx4 v[218:219], off
	s_waitcnt lgkmcnt(4)
	v_mfma_f32_32x32x16_bf16 v[4:19], v[160:163], v[198:201], v[4:19]
	v_exp_f32_e32 v68, v68
	v_exp_f32_e32 v69, v69
	v_exp_f32_e32 v70, v70
	v_exp_f32_e32 v71, v71
	v_mfma_f32_32x32x16_bf16 v[20:35], v[160:163], v[202:205], v[20:35]
	v_exp_f32_e32 v72, v72
	v_exp_f32_e32 v73, v73
	v_exp_f32_e32 v74, v74
	v_exp_f32_e32 v75, v75
	v_add_u32_e32 v96, s23, v189
	ds_read_b128 v[84:87], v96
	ds_read_b128 v[168:171], v96 offset:512
	v_mfma_f32_32x32x16_bf16 v[4:19], v[156:159], v[100:103], v[4:19]
	v_exp_f32_e32 v76, v76
	v_exp_f32_e32 v77, v77
	v_exp_f32_e32 v78, v78
	v_exp_f32_e32 v79, v79
	ds_read_b128 v[172:175], v96 offset:2048
	ds_read_b128 v[164:167], v96 offset:2560
	v_mfma_f32_32x32x16_bf16 v[20:35], v[156:159], v[104:107], v[20:35]
	v_exp_f32_e32 v80, v80
	v_exp_f32_e32 v81, v81
	v_exp_f32_e32 v82, v82
	v_exp_f32_e32 v83, v83
	ds_read_b128 v[128:131], v96 offset:4096
	ds_read_b128 v[124:127], v96 offset:4608
	v_mfma_f32_32x32x16_bf16 v[4:19], v[148:151], v[108:111], v[4:19]
	v_exp_f32_e32 v52, v52
	v_exp_f32_e32 v53, v53
	v_exp_f32_e32 v54, v54
	v_exp_f32_e32 v55, v55
	ds_read_b128 v[120:123], v96 offset:6144
	ds_read_b128 v[116:119], v96 offset:6656
	v_mfma_f32_32x32x16_bf16 v[20:35], v[148:151], v[112:115], v[20:35]
	v_exp_f32_e32 v56, v56
	v_exp_f32_e32 v57, v57
	v_exp_f32_e32 v58, v58
	v_exp_f32_e32 v59, v59
	s_waitcnt lgkmcnt(8)
	v_mfma_f32_32x32x16_bf16 v[4:19], v[140:143], v[88:91], v[4:19]
	v_exp_f32_e32 v60, v60
	v_exp_f32_e32 v61, v61
	v_exp_f32_e32 v62, v62
	v_exp_f32_e32 v63, v63
	v_mfma_f32_32x32x16_bf16 v[20:35], v[140:143], v[92:95], v[20:35]
	v_exp_f32_e32 v64, v64
	v_exp_f32_e32 v65, v65
	v_exp_f32_e32 v66, v66
	v_exp_f32_e32 v67, v67
	s_add_i32 s26, s23, 0x2000
	s_and_b32 s16, s21, 0xfc000
	s_lshl_b32 s16, s16, 1
	v_lshl_add_u64 v[218:219], v[180:181], 0, s[16:17]
	s_add_i32 m0, s23, s8
	s_nop 0
	global_load_lds_dwordx4 v[218:219], off
	s_cmpk_lg_i32 s23, 0x4000
	v_add_f32_e32 v88, v191, v179
	s_mov_b32 s16, s15
	s_cselect_b32 s15, s26, 0
	s_add_i32 s14, s14, 2
	s_add_i32 s21, s21, 0x8000
	s_add_i32 s20, s20, 0x8000
	s_mov_b32 s22, s23
	v_add_f32_e32 v191, v88, v190
	s_cmp_gt_u32 s14, 56
	s_waitcnt vmcnt(2) lgkmcnt(0)
	s_barrier
	s_cbranch_scc0 .LBB0_479
;   #define RESC() do{ if(resc){ asm volatile("s_waitcnt lgkmcnt(0)":::"memory"); \
;       _Pragma("unroll") for(int d_=0;d_<2;++d_) _Pragma("unroll") for(int r=0;r<16;++r)o[d_][r]*=wsf[crow(r,hi)]; } }while(0)
;   #define ROT() do{sl_prev=sl_cur;sl_cur=sl_next;sl_next=(sl_next==(NSLOT-1)*SLOTB)?0:sl_next+SLOTB;}while(0)
;   #define ENDW(tt) do{ if((tt)+3<NT){WAIT_BAR(2);} else if((tt)+2<NT){WAIT_BAR(1);} else {WAIT_BAR(0);} }while(0)
; template<int THRL,bool NOMAX> __device__ __forceinline__ void attn_unit(int b,int h,int qb,int t0,const bf16*Q,const bf16*__restrict__ KV,const bf16*__restrict__ GA,bf16*O,char*shm){
;     ...
;   for(;t+1<NT;t+=2){
;     STEP(pB0,pB1,pA0,pA1,t,(t+3<NT),(t+1<NT),(t+1<NT));       ENDW(t);   RESC(); ROT();
;     STEP(pA0,pA1,pB0,pB1,t+1,(t+4<NT),(t+2<NT),(t+2<NT));     ENDW(t+1); RESC(); ROT();
	s_and_b32 s12, s12, 0x3fffffc0
	s_cmp_lg_u32 0, -1
	s_cselect_b32 s14, 0, 0
	s_add_i32 s15, s14, 0x6000
	s_lshl_b32 s12, s12, 2
	v_add_u32_e32 v88, s15, v177
	s_add_i32 s12, s12, 0
	v_add3_u32 v190, v88, v176, v178
	ds_read_b64_tr_b16 v[198:199], v2 offset:32768
	ds_read_b64_tr_b16 v[200:201], v2 offset:33280
	v_add_f32_e32 v88, v68, v69
	v_add_f32_e32 v88, v70, v88
	v_add_f32_e32 v88, v71, v88
	v_add_f32_e32 v88, v72, v88
	v_add_f32_e32 v88, v73, v88
	v_cvt_pk_bf16_f32 v160, v68, v69
	v_cvt_pk_bf16_f32 v161, v70, v71
	s_waitcnt lgkmcnt(9)
	v_mfma_f32_32x32x16_bf16 v[100:115], v[84:87], v[152:155], v[36:51]
	ds_read_b64_tr_b16 v[176:177], v2 offset:36864
	ds_read_b64_tr_b16 v[178:179], v2 offset:37376
	v_add_f32_e32 v68, v74, v88
	v_add_f32_e32 v68, v75, v68
	v_add_f32_e32 v68, v76, v68
	v_add_f32_e32 v140, v77, v68
	v_cvt_pk_bf16_f32 v162, v72, v73
	v_cvt_pk_bf16_f32 v163, v74, v75
	s_waitcnt lgkmcnt(10)
	v_mfma_f32_32x32x16_bf16 v[84:99], v[168:171], v[152:155], v[36:51]
	ds_read_b64_tr_b16 v[68:69], v2 offset:33792
	ds_read_b64_tr_b16 v[70:71], v2 offset:34304
	v_add_f32_e32 v72, v78, v140
	v_add_f32_e32 v72, v79, v72
	v_add_f32_e32 v72, v80, v72
	v_add_f32_e32 v140, v81, v72
	v_cvt_pk_bf16_f32 v156, v76, v77
	v_cvt_pk_bf16_f32 v157, v78, v79
	s_waitcnt lgkmcnt(11)
	v_mfma_f32_32x32x16_bf16 v[100:115], v[172:175], v[144:147], v[100:115]
	ds_read_b64_tr_b16 v[72:73], v2 offset:37888
	ds_read_b64_tr_b16 v[74:75], v2 offset:38400
	v_add_f32_e32 v76, v82, v140
	v_add_f32_e32 v76, v83, v76
	v_add_f32_e32 v76, v52, v76
	v_add_f32_e32 v140, v53, v76
	v_cvt_pk_bf16_f32 v158, v80, v81
	v_cvt_pk_bf16_f32 v159, v82, v83
	s_waitcnt lgkmcnt(12)
	v_mfma_f32_32x32x16_bf16 v[84:99], v[164:167], v[144:147], v[84:99]
	ds_read_b64_tr_b16 v[76:77], v2 offset:34816
	ds_read_b64_tr_b16 v[78:79], v2 offset:35328
	v_add_f32_e32 v80, v54, v140
	v_add_f32_e32 v80, v55, v80
	v_add_f32_e32 v80, v56, v80
	v_add_f32_e32 v80, v57, v80
	v_cvt_pk_bf16_f32 v148, v52, v53
	v_cvt_pk_bf16_f32 v149, v54, v55
	s_waitcnt lgkmcnt(13)
	v_mfma_f32_32x32x16_bf16 v[100:115], v[128:131], v[136:139], v[100:115]
	ds_read_b64_tr_b16 v[52:53], v2 offset:38912
	ds_read_b64_tr_b16 v[54:55], v2 offset:39424
	v_add_f32_e32 v80, v58, v80
	v_add_f32_e32 v80, v59, v80
	v_add_f32_e32 v80, v60, v80
	v_add_f32_e32 v80, v61, v80
	v_cvt_pk_bf16_f32 v150, v56, v57
	v_cvt_pk_bf16_f32 v151, v58, v59
	s_waitcnt lgkmcnt(14)
	v_mfma_f32_32x32x16_bf16 v[84:99], v[124:127], v[136:139], v[84:99]
	ds_read_b64_tr_b16 v[56:57], v2 offset:35840
	ds_read_b64_tr_b16 v[58:59], v2 offset:36352
	v_add_f32_e32 v80, v62, v80
	v_add_f32_e32 v80, v63, v80
	v_add_f32_e32 v80, v64, v80
	v_add_f32_e32 v80, v65, v80
	v_cvt_pk_bf16_f32 v140, v60, v61
	v_cvt_pk_bf16_f32 v141, v62, v63
	s_waitcnt lgkmcnt(14)
	v_mfma_f32_32x32x16_bf16 v[100:115], v[120:123], v[132:135], v[100:115]
	ds_read_b64_tr_b16 v[60:61], v2 offset:39936
	ds_read_b64_tr_b16 v[62:63], v2 offset:40448
	v_add_f32_e32 v80, v66, v80
	v_add_f32_e32 v80, v67, v80
	v_add_f32_e32 v80, 0, v80
	v_cvt_pk_bf16_f32 v142, v64, v65
	v_cvt_pk_bf16_f32 v143, v66, v67
	v_mfma_f32_32x32x16_bf16 v[84:99], v[116:119], v[132:135], v[84:99]
	v_readlane_b32 s20, v254, 56
	v_readlane_b32 s21, v254, 57
	s_mov_b32 s21, s17
	s_add_i32 s13, s14, s13
	v_lshl_add_u64 v[64:65], v[182:183], 0, s[20:21]
	s_add_i32 s14, s13, 0x4000
	s_mov_b32 s15, m0
	s_mov_b32 m0, s14
	s_nop 0
	global_load_lds_dwordx4 v[64:65], off
	s_mov_b32 m0, s15
	v_add_f32_e32 v191, v191, v80
	v_readlane_b32 s14, v254, 58
	v_readlane_b32 s15, v254, 59
	s_mov_b32 s15, s17
	s_mov_b32 s16, s14
	v_lshl_add_u64 v[64:65], v[180:181], 0, s[14:15]
	s_mov_b32 s14, m0
	s_mov_b32 m0, s8
	s_nop 0
	global_load_lds_dwordx4 v[64:65], off
	s_mov_b32 m0, s14
	v_writelane_b32 v254, s16, 58
	s_nop 1
	v_writelane_b32 v254, s17, 59
	s_waitcnt lgkmcnt(14)
	v_mfma_f32_32x32x16_bf16 v[4:19], v[160:163], v[198:201], v[4:19]
	v_exp_f32_e32 v100, v100
	v_exp_f32_e32 v101, v101
	v_exp_f32_e32 v102, v102
	v_exp_f32_e32 v103, v103
	s_waitcnt lgkmcnt(12)
	v_mfma_f32_32x32x16_bf16 v[20:35], v[160:163], v[176:179], v[20:35]
	v_exp_f32_e32 v104, v104
	v_exp_f32_e32 v105, v105
	v_exp_f32_e32 v106, v106
	v_exp_f32_e32 v107, v107
	ds_read_b128 v[64:67], v189
	ds_read_b128 v[80:83], v189 offset:512
	s_waitcnt lgkmcnt(12)
	v_mfma_f32_32x32x16_bf16 v[4:19], v[156:159], v[68:71], v[4:19]
	v_exp_f32_e32 v108, v108
	v_exp_f32_e32 v109, v109
	v_exp_f32_e32 v110, v110
	v_exp_f32_e32 v111, v111
	ds_read_b128 v[164:167], v189 offset:2048
	ds_read_b128 v[168:171], v189 offset:2560
	s_waitcnt lgkmcnt(12)
	v_mfma_f32_32x32x16_bf16 v[20:35], v[156:159], v[72:75], v[20:35]
	v_exp_f32_e32 v112, v112
	v_exp_f32_e32 v113, v113
	v_exp_f32_e32 v114, v114
	v_exp_f32_e32 v115, v115
	ds_read_b128 v[172:175], v189 offset:4096
	ds_read_b128 v[176:179], v189 offset:4608
	s_waitcnt lgkmcnt(12)
	v_mfma_f32_32x32x16_bf16 v[4:19], v[148:151], v[76:79], v[4:19]
	v_exp_f32_e32 v84, v84
	v_exp_f32_e32 v85, v85
	v_exp_f32_e32 v86, v86
	v_exp_f32_e32 v87, v87
	ds_read_b128 v[198:201], v189 offset:6144
	ds_read_b128 v[72:75], v189 offset:6656
	s_waitcnt lgkmcnt(12)
	v_mfma_f32_32x32x16_bf16 v[20:35], v[148:151], v[52:55], v[20:35]
	v_exp_f32_e32 v88, v88
	v_exp_f32_e32 v89, v89
	v_exp_f32_e32 v90, v90
	v_exp_f32_e32 v91, v91
	s_waitcnt lgkmcnt(10)
	v_mfma_f32_32x32x16_bf16 v[4:19], v[140:143], v[56:59], v[4:19]
	v_exp_f32_e32 v92, v92
	v_exp_f32_e32 v93, v93
	v_exp_f32_e32 v94, v94
	v_exp_f32_e32 v95, v95
	s_waitcnt lgkmcnt(8)
	v_mfma_f32_32x32x16_bf16 v[20:35], v[140:143], v[60:63], v[20:35]
	v_exp_f32_e32 v96, v96
	v_exp_f32_e32 v97, v97
	v_exp_f32_e32 v98, v98
	v_exp_f32_e32 v99, v99
	s_waitcnt vmcnt(2) lgkmcnt(0)
	s_barrier
;   #define RESC() do{ if(resc){ asm volatile("s_waitcnt lgkmcnt(0)":::"memory"); \
;       _Pragma("unroll") for(int d_=0;d_<2;++d_) _Pragma("unroll") for(int r=0;r<16;++r)o[d_][r]*=wsf[crow(r,hi)]; } }while(0)
;   #define ROT() do{sl_prev=sl_cur;sl_cur=sl_next;sl_next=(sl_next==(NSLOT-1)*SLOTB)?0:sl_next+SLOTB;}while(0)
;   #define ENDW(tt) do{ if((tt)+3<NT){WAIT_BAR(2);} else if((tt)+2<NT){WAIT_BAR(1);} else {WAIT_BAR(0);} }while(0)
; template<int THRL,bool NOMAX> __device__ __forceinline__ void attn_unit(int b,int h,int qb,int t0,const bf16*Q,const bf16*__restrict__ KV,const bf16*__restrict__ GA,bf16*O,char*shm){
;     ...
;   for(;t+1<NT;t+=2){
;     STEP(pB0,pB1,pA0,pA1,t,(t+3<NT),(t+1<NT),(t+1<NT));       ENDW(t);   RESC(); ROT();
;     STEP(pA0,pA1,pB0,pB1,t+1,(t+4<NT),(t+2<NT),(t+2<NT));     ENDW(t+1); RESC(); ROT();
	ds_read_b64_tr_b16 v[202:203], v2 offset:40960
	ds_read_b64_tr_b16 v[204:205], v2 offset:41472
	v_add_f32_e32 v52, v100, v101
	v_add_f32_e32 v52, v102, v52
	v_add_f32_e32 v52, v103, v52
	v_add_f32_e32 v52, v104, v52
	v_add_f32_e32 v52, v105, v52
	v_cvt_pk_bf16_f32 v160, v100, v101
	v_cvt_pk_bf16_f32 v161, v102, v103
	s_waitcnt lgkmcnt(9)
	v_mfma_f32_32x32x16_bf16 v[116:131], v[64:67], v[152:155], v[36:51]
	ds_read_b64_tr_b16 v[100:101], v2 offset:45056
	ds_read_b64_tr_b16 v[102:103], v2 offset:45568
	v_add_f32_e32 v52, v106, v52
	v_add_f32_e32 v52, v107, v52
	v_add_f32_e32 v52, v108, v52
	v_add_f32_e32 v76, v109, v52
	v_cvt_pk_bf16_f32 v162, v104, v105
	v_cvt_pk_bf16_f32 v163, v106, v107
	s_waitcnt lgkmcnt(10)
	v_mfma_f32_32x32x16_bf16 v[52:67], v[80:83], v[152:155], v[36:51]
	ds_read_b64_tr_b16 v[68:69], v2 offset:41984
	ds_read_b64_tr_b16 v[70:71], v2 offset:42496
	v_add_f32_e32 v76, v110, v76
	v_add_f32_e32 v76, v111, v76
	v_add_f32_e32 v76, v112, v76
	v_add_f32_e32 v80, v113, v76
	v_cvt_pk_bf16_f32 v156, v108, v109
	v_cvt_pk_bf16_f32 v157, v110, v111
	s_waitcnt lgkmcnt(11)
	v_mfma_f32_32x32x16_bf16 v[116:131], v[164:167], v[144:147], v[116:131]
	ds_read_b64_tr_b16 v[76:77], v2 offset:46080
	ds_read_b64_tr_b16 v[78:79], v2 offset:46592
	v_add_f32_e32 v80, v114, v80
	v_add_f32_e32 v80, v115, v80
	v_add_f32_e32 v80, v84, v80
	v_add_f32_e32 v104, v85, v80
	v_cvt_pk_bf16_f32 v158, v112, v113
	v_cvt_pk_bf16_f32 v159, v114, v115
	s_waitcnt lgkmcnt(12)
	v_mfma_f32_32x32x16_bf16 v[52:67], v[168:171], v[144:147], v[52:67]
	ds_read_b64_tr_b16 v[80:81], v2 offset:43008
	ds_read_b64_tr_b16 v[82:83], v2 offset:43520
	v_add_f32_e32 v104, v86, v104
	v_add_f32_e32 v104, v87, v104
	v_add_f32_e32 v104, v88, v104
	v_add_f32_e32 v108, v89, v104
	v_cvt_pk_bf16_f32 v148, v84, v85
	v_cvt_pk_bf16_f32 v149, v86, v87
	s_waitcnt lgkmcnt(13)
	v_mfma_f32_32x32x16_bf16 v[116:131], v[172:175], v[136:139], v[116:131]
	ds_read_b64_tr_b16 v[104:105], v2 offset:47104
	ds_read_b64_tr_b16 v[106:107], v2 offset:47616
	v_add_f32_e32 v84, v90, v108
	v_add_f32_e32 v84, v91, v84
	v_add_f32_e32 v84, v92, v84
	v_add_f32_e32 v84, v93, v84
	v_cvt_pk_bf16_f32 v150, v88, v89
	v_cvt_pk_bf16_f32 v151, v90, v91
	s_waitcnt lgkmcnt(14)
	v_mfma_f32_32x32x16_bf16 v[52:67], v[176:179], v[136:139], v[52:67]
	ds_read_b64_tr_b16 v[88:89], v2 offset:44032
	ds_read_b64_tr_b16 v[90:91], v2 offset:44544
	v_add_f32_e32 v84, v94, v84
	v_add_f32_e32 v84, v95, v84
	v_add_f32_e32 v84, v96, v84
	v_add_f32_e32 v84, v97, v84
	v_cvt_pk_bf16_f32 v140, v92, v93
	v_cvt_pk_bf16_f32 v141, v94, v95
	s_waitcnt lgkmcnt(14)
	v_mfma_f32_32x32x16_bf16 v[116:131], v[198:201], v[132:135], v[116:131]
	ds_read_b64_tr_b16 v[92:93], v2 offset:48128
	ds_read_b64_tr_b16 v[94:95], v2 offset:48640
	v_mfma_f32_32x32x16_bf16 v[52:67], v[72:75], v[132:135], v[52:67]
	v_add_f32_e32 v72, v98, v84
	v_add_f32_e32 v72, v99, v72
	v_add_f32_e32 v72, 0, v72
	v_cvt_pk_bf16_f32 v142, v96, v97
	v_cvt_pk_bf16_f32 v143, v98, v99
	v_readlane_b32 s22, v254, 60
	v_readlane_b32 s23, v254, 61
	s_mov_b32 s23, s17
	v_add_f32_e32 v191, v191, v72
	v_lshl_add_u64 v[72:73], v[182:183], 0, s[22:23]
	s_mov_b32 s14, m0
	s_mov_b32 m0, s9
	s_nop 0
	global_load_lds_dwordx4 v[72:73], off
	s_mov_b32 m0, s14
	s_add_i32 s9, s13, 0x8000
	v_readlane_b32 s14, v254, 62
	v_readlane_b32 s15, v254, 63
	s_mov_b32 s15, s17
	s_mov_b32 s16, s14
	v_lshl_add_u64 v[72:73], v[180:181], 0, s[14:15]
	s_mov_b32 s14, m0
	s_mov_b32 m0, s9
	s_nop 0
	global_load_lds_dwordx4 v[72:73], off
	s_mov_b32 m0, s14
	v_writelane_b32 v254, s16, 62
	s_nop 1
	v_writelane_b32 v254, s17, 63
	s_waitcnt lgkmcnt(14)
	v_mfma_f32_32x32x16_bf16 v[4:19], v[160:163], v[202:205], v[4:19]
	v_exp_f32_e32 v116, v116
	v_exp_f32_e32 v117, v117
	v_exp_f32_e32 v118, v118
	v_exp_f32_e32 v119, v119
	s_waitcnt lgkmcnt(12)
	v_mfma_f32_32x32x16_bf16 v[20:35], v[160:163], v[100:103], v[20:35]
	v_exp_f32_e32 v120, v120
	v_exp_f32_e32 v121, v121
	v_exp_f32_e32 v122, v122
	v_exp_f32_e32 v123, v123
	ds_read_b128 v[72:75], v189 offset:8192
	ds_read_b128 v[96:99], v189 offset:8704
	s_waitcnt lgkmcnt(12)
	v_mfma_f32_32x32x16_bf16 v[4:19], v[156:159], v[68:71], v[4:19]
	v_exp_f32_e32 v124, v124
	v_exp_f32_e32 v125, v125
	v_exp_f32_e32 v126, v126
	v_exp_f32_e32 v127, v127
	ds_read_b128 v[164:167], v189 offset:10240
	ds_read_b128 v[168:171], v189 offset:10752
	s_waitcnt lgkmcnt(12)
	v_mfma_f32_32x32x16_bf16 v[20:35], v[156:159], v[76:79], v[20:35]
	v_exp_f32_e32 v128, v128
	v_exp_f32_e32 v129, v129
	v_exp_f32_e32 v130, v130
	v_exp_f32_e32 v131, v131
	ds_read_b128 v[172:175], v189 offset:12288
	ds_read_b128 v[176:179], v189 offset:12800
	s_waitcnt lgkmcnt(12)
	v_mfma_f32_32x32x16_bf16 v[4:19], v[148:151], v[80:83], v[4:19]
	v_exp_f32_e32 v52, v52
	v_exp_f32_e32 v53, v53
	v_exp_f32_e32 v54, v54
	v_exp_f32_e32 v55, v55
	ds_read_b128 v[198:201], v189 offset:14336
	ds_read_b128 v[84:87], v189 offset:14848
	s_waitcnt lgkmcnt(12)
	v_mfma_f32_32x32x16_bf16 v[20:35], v[148:151], v[104:107], v[20:35]
	v_exp_f32_e32 v56, v56
	v_exp_f32_e32 v57, v57
	v_exp_f32_e32 v58, v58
	v_exp_f32_e32 v59, v59
	s_waitcnt lgkmcnt(10)
	v_mfma_f32_32x32x16_bf16 v[4:19], v[140:143], v[88:91], v[4:19]
	v_exp_f32_e32 v60, v60
	v_exp_f32_e32 v61, v61
	v_exp_f32_e32 v62, v62
	v_exp_f32_e32 v63, v63
	s_waitcnt lgkmcnt(8)
	v_mfma_f32_32x32x16_bf16 v[20:35], v[140:143], v[92:95], v[20:35]
	v_exp_f32_e32 v64, v64
	v_exp_f32_e32 v65, v65
	v_exp_f32_e32 v66, v66
	v_exp_f32_e32 v67, v67
	s_waitcnt vmcnt(2) lgkmcnt(0)
	s_barrier
;   #define RESC() do{ if(resc){ asm volatile("s_waitcnt lgkmcnt(0)":::"memory"); \
;       _Pragma("unroll") for(int d_=0;d_<2;++d_) _Pragma("unroll") for(int r=0;r<16;++r)o[d_][r]*=wsf[crow(r,hi)]; } }while(0)
;   #define ROT() do{sl_prev=sl_cur;sl_cur=sl_next;sl_next=(sl_next==(NSLOT-1)*SLOTB)?0:sl_next+SLOTB;}while(0)
;   #define ENDW(tt) do{ if((tt)+3<NT){WAIT_BAR(2);} else if((tt)+2<NT){WAIT_BAR(1);} else {WAIT_BAR(0);} }while(0)
; template<int THRL,bool NOMAX> __device__ __forceinline__ void attn_unit(int b,int h,int qb,int t0,const bf16*Q,const bf16*__restrict__ KV,const bf16*__restrict__ GA,bf16*O,char*shm){
;     ...
;   for(;t+1<NT;t+=2){
;     STEP(pB0,pB1,pA0,pA1,t,(t+3<NT),(t+1<NT),(t+1<NT));       ENDW(t);   RESC(); ROT();
;     STEP(pA0,pA1,pB0,pB1,t+1,(t+4<NT),(t+2<NT),(t+2<NT));     ENDW(t+1); RESC(); ROT();
	ds_read_b64_tr_b16 v[88:89], v2 offset:24576
	ds_read_b64_tr_b16 v[90:91], v2 offset:25088
	v_add_f32_e32 v68, v116, v117
	v_add_f32_e32 v68, v118, v68
	v_add_f32_e32 v68, v119, v68
	v_add_f32_e32 v68, v120, v68
	v_add_f32_e32 v68, v121, v68
	v_cvt_pk_bf16_f32 v160, v116, v117
	v_cvt_pk_bf16_f32 v161, v118, v119
	s_waitcnt lgkmcnt(9)
	v_mfma_f32_32x32x16_bf16 v[100:115], v[72:75], v[152:155], v[36:51]
	ds_read_b64_tr_b16 v[92:93], v2 offset:28672
	ds_read_b64_tr_b16 v[94:95], v2 offset:29184
	v_add_f32_e32 v68, v122, v68
	v_add_f32_e32 v68, v123, v68
	v_add_f32_e32 v68, v124, v68
	v_add_f32_e32 v116, v125, v68
	v_cvt_pk_bf16_f32 v162, v120, v121
	v_cvt_pk_bf16_f32 v163, v122, v123
	s_waitcnt lgkmcnt(10)
	v_mfma_f32_32x32x16_bf16 v[68:83], v[96:99], v[152:155], v[36:51]
	ds_read_b64_tr_b16 v[96:97], v2 offset:25600
	ds_read_b64_tr_b16 v[98:99], v2 offset:26112
	v_add_f32_e32 v116, v126, v116
	v_add_f32_e32 v116, v127, v116
	v_add_f32_e32 v116, v128, v116
	v_add_f32_e32 v120, v129, v116
	v_cvt_pk_bf16_f32 v156, v124, v125
	v_cvt_pk_bf16_f32 v157, v126, v127
	s_waitcnt lgkmcnt(11)
	v_mfma_f32_32x32x16_bf16 v[100:115], v[164:167], v[144:147], v[100:115]
	ds_read_b64_tr_b16 v[116:117], v2 offset:29696
	ds_read_b64_tr_b16 v[118:119], v2 offset:30208
	v_add_f32_e32 v120, v130, v120
	v_add_f32_e32 v120, v131, v120
	v_add_f32_e32 v120, v52, v120
	v_add_f32_e32 v124, v53, v120
	v_cvt_pk_bf16_f32 v158, v128, v129
	v_cvt_pk_bf16_f32 v159, v130, v131
	s_waitcnt lgkmcnt(12)
	v_mfma_f32_32x32x16_bf16 v[68:83], v[168:171], v[144:147], v[68:83]
	ds_read_b64_tr_b16 v[120:121], v2 offset:26624
	ds_read_b64_tr_b16 v[122:123], v2 offset:27136
	v_add_f32_e32 v124, v54, v124
	v_add_f32_e32 v124, v55, v124
	v_add_f32_e32 v124, v56, v124
	v_add_f32_e32 v124, v57, v124
	v_cvt_pk_bf16_f32 v148, v52, v53
	v_cvt_pk_bf16_f32 v149, v54, v55
	s_waitcnt lgkmcnt(13)
	v_mfma_f32_32x32x16_bf16 v[100:115], v[172:175], v[136:139], v[100:115]
	ds_read_b64_tr_b16 v[52:53], v2 offset:30720
	ds_read_b64_tr_b16 v[54:55], v2 offset:31232
	v_add_f32_e32 v124, v58, v124
	v_add_f32_e32 v124, v59, v124
	v_add_f32_e32 v124, v60, v124
	v_add_f32_e32 v124, v61, v124
	v_cvt_pk_bf16_f32 v150, v56, v57
	v_cvt_pk_bf16_f32 v151, v58, v59
	s_waitcnt lgkmcnt(14)
	v_mfma_f32_32x32x16_bf16 v[68:83], v[176:179], v[136:139], v[68:83]
	ds_read_b64_tr_b16 v[56:57], v2 offset:27648
	ds_read_b64_tr_b16 v[58:59], v2 offset:28160
	v_add_f32_e32 v124, v62, v124
	v_add_f32_e32 v124, v63, v124
	v_add_f32_e32 v124, v64, v124
	v_add_f32_e32 v124, v65, v124
	v_cvt_pk_bf16_f32 v140, v60, v61
	v_cvt_pk_bf16_f32 v141, v62, v63
	s_waitcnt lgkmcnt(14)
	v_mfma_f32_32x32x16_bf16 v[100:115], v[198:201], v[132:135], v[100:115]
	ds_read_b64_tr_b16 v[60:61], v2 offset:31744
	ds_read_b64_tr_b16 v[62:63], v2 offset:32256
	v_mfma_f32_32x32x16_bf16 v[68:83], v[84:87], v[132:135], v[68:83]
	v_add_f32_e32 v84, v66, v124
	v_add_f32_e32 v84, v67, v84
	v_add_f32_e32 v84, 0, v84
	v_cvt_pk_bf16_f32 v142, v64, v65
	v_cvt_pk_bf16_f32 v143, v66, v67
	s_mov_b32 s14, s20
	v_lshl_add_u64 v[64:65], v[180:181], 0, s[20:21]
	s_add_i32 s13, s13, 0xa000
	s_mov_b32 s9, m0
	s_mov_b32 m0, s13
	s_nop 0
	global_load_lds_dwordx4 v[64:65], off
	s_mov_b32 m0, s9
	v_writelane_b32 v254, s14, 56
	v_add_f32_e32 v182, v191, v84
	s_nop 0
	v_writelane_b32 v254, s15, 57
	s_waitcnt lgkmcnt(14)
	v_mfma_f32_32x32x16_bf16 v[4:19], v[160:163], v[88:91], v[4:19]
	v_exp_f32_e32 v100, v100
	v_exp_f32_e32 v101, v101
	v_exp_f32_e32 v102, v102
	v_exp_f32_e32 v103, v103
	s_waitcnt lgkmcnt(12)
	v_mfma_f32_32x32x16_bf16 v[20:35], v[160:163], v[92:95], v[20:35]
	v_exp_f32_e32 v104, v104
	v_exp_f32_e32 v105, v105
	v_exp_f32_e32 v106, v106
	v_exp_f32_e32 v107, v107
	ds_read_b128 v[64:67], v189 offset:16384
	ds_read_b128 v[124:127], v189 offset:16896
	s_waitcnt lgkmcnt(12)
	v_mfma_f32_32x32x16_bf16 v[4:19], v[156:159], v[96:99], v[4:19]
	v_exp_f32_e32 v108, v108
	v_exp_f32_e32 v109, v109
	v_exp_f32_e32 v110, v110
	v_exp_f32_e32 v111, v111
	ds_read_b128 v[128:131], v189 offset:18432
	ds_read_b128 v[164:167], v189 offset:18944
	s_waitcnt lgkmcnt(12)
	v_mfma_f32_32x32x16_bf16 v[20:35], v[156:159], v[116:119], v[20:35]
	v_exp_f32_e32 v112, v112
	v_exp_f32_e32 v113, v113
	v_exp_f32_e32 v114, v114
	v_exp_f32_e32 v115, v115
	ds_read_b128 v[168:171], v189 offset:20480
	ds_read_b128 v[172:175], v189 offset:20992
	s_waitcnt lgkmcnt(12)
	v_mfma_f32_32x32x16_bf16 v[4:19], v[148:151], v[120:123], v[4:19]
	v_exp_f32_e32 v68, v68
	v_exp_f32_e32 v69, v69
	v_exp_f32_e32 v70, v70
	v_exp_f32_e32 v71, v71
	ds_read_b128 v[120:123], v189 offset:22528
	ds_read_b128 v[116:119], v189 offset:23040
	s_waitcnt lgkmcnt(12)
	v_mfma_f32_32x32x16_bf16 v[20:35], v[148:151], v[52:55], v[20:35]
	v_exp_f32_e32 v72, v72
	v_exp_f32_e32 v73, v73
	v_exp_f32_e32 v74, v74
	v_exp_f32_e32 v75, v75
	s_waitcnt lgkmcnt(10)
	v_mfma_f32_32x32x16_bf16 v[4:19], v[140:143], v[56:59], v[4:19]
	v_exp_f32_e32 v76, v76
	v_exp_f32_e32 v77, v77
	v_exp_f32_e32 v78, v78
	v_exp_f32_e32 v79, v79
	s_waitcnt lgkmcnt(8)
	v_mfma_f32_32x32x16_bf16 v[20:35], v[140:143], v[60:63], v[20:35]
	v_exp_f32_e32 v80, v80
	v_exp_f32_e32 v81, v81
	v_exp_f32_e32 v82, v82
	v_exp_f32_e32 v83, v83
	s_waitcnt vmcnt(1) lgkmcnt(0)
	s_barrier
;   #define RESC() do{ if(resc){ asm volatile("s_waitcnt lgkmcnt(0)":::"memory"); \
;       _Pragma("unroll") for(int d_=0;d_<2;++d_) _Pragma("unroll") for(int r=0;r<16;++r)o[d_][r]*=wsf[crow(r,hi)]; } }while(0)
;   #define ROT() do{sl_prev=sl_cur;sl_cur=sl_next;sl_next=(sl_next==(NSLOT-1)*SLOTB)?0:sl_next+SLOTB;}while(0)
;   #define ENDW(tt) do{ if((tt)+3<NT){WAIT_BAR(2);} else if((tt)+2<NT){WAIT_BAR(1);} else {WAIT_BAR(0);} }while(0)
; template<int THRL,bool NOMAX> __device__ __forceinline__ void attn_unit(int b,int h,int qb,int t0,const bf16*Q,const bf16*__restrict__ KV,const bf16*__restrict__ GA,bf16*O,char*shm){
;     ...
;   for(;t+1<NT;t+=2){
;     STEP(pB0,pB1,pA0,pA1,t,(t+3<NT),(t+1<NT),(t+1<NT));       ENDW(t);   RESC(); ROT();
;     STEP(pA0,pA1,pB0,pB1,t+1,(t+4<NT),(t+2<NT),(t+2<NT));     ENDW(t+1); RESC(); ROT();
	ds_read_b64_tr_b16 v[176:177], v2 offset:32768
	ds_read_b64_tr_b16 v[178:179], v2 offset:33280
	v_add_f32_e32 v52, v100, v101
	v_add_f32_e32 v52, v102, v52
	v_add_f32_e32 v52, v103, v52
	v_add_f32_e32 v52, v104, v52
	v_add_f32_e32 v52, v105, v52
	v_cvt_pk_bf16_f32 v160, v100, v101
	v_cvt_pk_bf16_f32 v161, v102, v103
	s_waitcnt lgkmcnt(9)
	v_mfma_f32_32x32x16_bf16 v[84:99], v[64:67], v[152:155], v[36:51]
	ds_read_b64_tr_b16 v[100:101], v2 offset:36864
	ds_read_b64_tr_b16 v[102:103], v2 offset:37376
	v_add_f32_e32 v52, v106, v52
	v_add_f32_e32 v52, v107, v52
	v_add_f32_e32 v52, v108, v52
	v_add_f32_e32 v140, v109, v52
	v_cvt_pk_bf16_f32 v162, v104, v105
	v_cvt_pk_bf16_f32 v163, v106, v107
	s_waitcnt lgkmcnt(10)
	v_mfma_f32_32x32x16_bf16 v[52:67], v[124:127], v[152:155], v[36:51]
	ds_read_b64_tr_b16 v[124:125], v2 offset:33792
	ds_read_b64_tr_b16 v[126:127], v2 offset:34304
	v_add_f32_e32 v104, v110, v140
	v_add_f32_e32 v104, v111, v104
	v_add_f32_e32 v104, v112, v104
	v_add_f32_e32 v104, v113, v104
	v_cvt_pk_bf16_f32 v156, v108, v109
	v_cvt_pk_bf16_f32 v157, v110, v111
	s_waitcnt lgkmcnt(11)
	v_mfma_f32_32x32x16_bf16 v[84:99], v[128:131], v[144:147], v[84:99]
	ds_read_b64_tr_b16 v[106:107], v2 offset:37888
	ds_read_b64_tr_b16 v[108:109], v2 offset:38400
	v_add_f32_e32 v104, v114, v104
	v_add_f32_e32 v104, v115, v104
	v_add_f32_e32 v104, v68, v104
	v_add_f32_e32 v104, v69, v104
	v_cvt_pk_bf16_f32 v158, v112, v113
	v_cvt_pk_bf16_f32 v159, v114, v115
	s_waitcnt lgkmcnt(12)
	v_mfma_f32_32x32x16_bf16 v[52:67], v[164:167], v[144:147], v[52:67]
	ds_read_b64_tr_b16 v[110:111], v2 offset:34816
	ds_read_b64_tr_b16 v[112:113], v2 offset:35328
	v_add_f32_e32 v104, v70, v104
	v_add_f32_e32 v104, v71, v104
	v_add_f32_e32 v104, v72, v104
	v_add_f32_e32 v104, v73, v104
	v_cvt_pk_bf16_f32 v148, v68, v69
	v_cvt_pk_bf16_f32 v149, v70, v71
	s_waitcnt lgkmcnt(13)
	v_mfma_f32_32x32x16_bf16 v[84:99], v[168:171], v[136:139], v[84:99]
	ds_read_b64_tr_b16 v[68:69], v2 offset:38912
	ds_read_b64_tr_b16 v[70:71], v2 offset:39424
	v_add_f32_e32 v104, v74, v104
	v_add_f32_e32 v104, v75, v104
	v_add_f32_e32 v104, v76, v104
	v_add_f32_e32 v104, v77, v104
	v_cvt_pk_bf16_f32 v150, v72, v73
	v_cvt_pk_bf16_f32 v151, v74, v75
	s_waitcnt lgkmcnt(14)
	v_mfma_f32_32x32x16_bf16 v[52:67], v[172:175], v[136:139], v[52:67]
	ds_read_b64_tr_b16 v[72:73], v2 offset:35840
	ds_read_b64_tr_b16 v[74:75], v2 offset:36352
	v_add_f32_e32 v104, v78, v104
	v_add_f32_e32 v104, v79, v104
	v_add_f32_e32 v104, v80, v104
	v_add_f32_e32 v104, v81, v104
	v_cvt_pk_bf16_f32 v140, v76, v77
	v_cvt_pk_bf16_f32 v141, v78, v79
	s_waitcnt lgkmcnt(14)
	v_mfma_f32_32x32x16_bf16 v[84:99], v[120:123], v[132:135], v[84:99]
	ds_read_b64_tr_b16 v[76:77], v2 offset:39936
	ds_read_b64_tr_b16 v[78:79], v2 offset:40448
	v_add_f32_e32 v104, v82, v104
	v_add_f32_e32 v104, v83, v104
	v_add_f32_e32 v104, 0, v104
	v_cvt_pk_bf16_f32 v142, v80, v81
	v_cvt_pk_bf16_f32 v143, v82, v83
	v_mfma_f32_32x32x16_bf16 v[52:67], v[116:119], v[132:135], v[52:67]
	s_mov_b32 s14, s22
	v_lshl_add_u64 v[80:81], v[180:181], 0, s[22:23]
	s_mov_b32 s9, m0
	s_mov_b32 m0, s8
	s_nop 0
	global_load_lds_dwordx4 v[80:81], off
	s_mov_b32 m0, s9
	v_writelane_b32 v254, s14, 60
	v_add_f32_e32 v104, v182, v104
	s_nop 0
	v_writelane_b32 v254, s15, 61
	s_waitcnt lgkmcnt(14)
	v_mfma_f32_32x32x16_bf16 v[4:19], v[160:163], v[176:179], v[4:19]
	v_exp_f32_e32 v84, v84
	v_exp_f32_e32 v85, v85
	v_exp_f32_e32 v86, v86
	v_exp_f32_e32 v87, v87
	s_waitcnt lgkmcnt(12)
	v_mfma_f32_32x32x16_bf16 v[20:35], v[160:163], v[100:103], v[20:35]
	v_exp_f32_e32 v88, v88
	v_exp_f32_e32 v89, v89
	v_exp_f32_e32 v90, v90
	v_exp_f32_e32 v91, v91
	ds_read_b128 v[114:117], v189
	ds_read_b128 v[118:121], v189 offset:512
	s_waitcnt lgkmcnt(12)
	v_mfma_f32_32x32x16_bf16 v[4:19], v[156:159], v[124:127], v[4:19]
	v_exp_f32_e32 v92, v92
	v_exp_f32_e32 v93, v93
	v_exp_f32_e32 v94, v94
	v_exp_f32_e32 v95, v95
	ds_read_b128 v[122:125], v189 offset:2048
	ds_read_b128 v[126:129], v189 offset:2560
	s_waitcnt lgkmcnt(12)
	v_mfma_f32_32x32x16_bf16 v[20:35], v[156:159], v[106:109], v[20:35]
	v_exp_f32_e32 v96, v96
	v_exp_f32_e32 v97, v97
	v_exp_f32_e32 v98, v98
	v_exp_f32_e32 v99, v99
	ds_read_b128 v[106:109], v189 offset:4096
	ds_read_b128 v[164:167], v189 offset:4608
	s_waitcnt lgkmcnt(12)
	v_mfma_f32_32x32x16_bf16 v[4:19], v[148:151], v[110:113], v[4:19]
	v_exp_f32_e32 v52, v52
	v_exp_f32_e32 v53, v53
	v_exp_f32_e32 v54, v54
	v_exp_f32_e32 v55, v55
	ds_read_b128 v[110:113], v189 offset:6144
	ds_read_b128 v[100:103], v189 offset:6656
	s_waitcnt lgkmcnt(12)
	v_mfma_f32_32x32x16_bf16 v[20:35], v[148:151], v[68:71], v[20:35]
	v_exp_f32_e32 v56, v56
	v_exp_f32_e32 v57, v57
	v_exp_f32_e32 v58, v58
	v_exp_f32_e32 v59, v59
	s_waitcnt lgkmcnt(10)
	v_mfma_f32_32x32x16_bf16 v[4:19], v[140:143], v[72:75], v[4:19]
	v_exp_f32_e32 v60, v60
	v_exp_f32_e32 v61, v61
	v_exp_f32_e32 v62, v62
	v_exp_f32_e32 v63, v63
	s_waitcnt lgkmcnt(8)
	v_mfma_f32_32x32x16_bf16 v[20:35], v[140:143], v[76:79], v[20:35]
	v_exp_f32_e32 v64, v64
	v_exp_f32_e32 v65, v65
	v_exp_f32_e32 v66, v66
	v_exp_f32_e32 v67, v67
	s_waitcnt vmcnt(0) lgkmcnt(0)
	s_barrier
;   #define RESC() do{ if(resc){ asm volatile("s_waitcnt lgkmcnt(0)":::"memory"); \
;       _Pragma("unroll") for(int d_=0;d_<2;++d_) _Pragma("unroll") for(int r=0;r<16;++r)o[d_][r]*=wsf[crow(r,hi)]; } }while(0)
; template<int THRL,bool NOMAX> __device__ __forceinline__ void attn_unit(int b,int h,int qb,int t0,const bf16*Q,const bf16*__restrict__ KV,const bf16*__restrict__ GA,bf16*O,char*shm){
;     ...
;   STEP(pB0,pB1,pA0,pA1,NT-1,false,false,false); RESC();
	ds_read_b64_tr_b16 v[168:169], v2 offset:40960
	ds_read_b64_tr_b16 v[170:171], v2 offset:41472
	v_add_f32_e32 v68, v84, v85
	v_add_f32_e32 v68, v86, v68
	v_add_f32_e32 v68, v87, v68
	v_add_f32_e32 v68, v88, v68
	v_add_f32_e32 v105, v89, v68
	v_cvt_pk_bf16_f32 v160, v84, v85
	v_cvt_pk_bf16_f32 v161, v86, v87
	s_waitcnt lgkmcnt(9)
	v_mfma_f32_32x32x16_bf16 v[68:83], v[114:117], v[152:155], v[36:51]
	ds_read_b64_tr_b16 v[84:85], v2 offset:45056
	ds_read_b64_tr_b16 v[86:87], v2 offset:45568
	s_waitcnt lgkmcnt(10)
	v_mfma_f32_32x32x16_bf16 v[36:51], v[118:121], v[152:155], v[36:51]
	v_add_f32_e32 v105, v90, v105
	v_add_f32_e32 v105, v91, v105
	v_add_f32_e32 v105, v92, v105
	v_add_f32_e32 v105, v93, v105
	v_cvt_pk_bf16_f32 v162, v88, v89
	v_cvt_pk_bf16_f32 v163, v90, v91
	ds_read_b64_tr_b16 v[88:89], v2 offset:41984
	ds_read_b64_tr_b16 v[90:91], v2 offset:42496
	v_add_f32_e32 v105, v94, v105
	v_add_f32_e32 v105, v95, v105
	v_add_f32_e32 v105, v96, v105
	v_add_f32_e32 v105, v97, v105
	v_cvt_pk_bf16_f32 v156, v92, v93
	v_cvt_pk_bf16_f32 v157, v94, v95
	s_waitcnt lgkmcnt(11)
	v_mfma_f32_32x32x16_bf16 v[68:83], v[122:125], v[144:147], v[68:83]
	ds_read_b64_tr_b16 v[92:93], v2 offset:46080
	ds_read_b64_tr_b16 v[94:95], v2 offset:46592
	s_waitcnt lgkmcnt(12)
	v_mfma_f32_32x32x16_bf16 v[36:51], v[126:129], v[144:147], v[36:51]
	v_add_f32_e32 v105, v98, v105
	v_add_f32_e32 v105, v99, v105
	v_add_f32_e32 v105, v52, v105
	v_add_f32_e32 v105, v53, v105
	v_cvt_pk_bf16_f32 v158, v96, v97
	v_cvt_pk_bf16_f32 v159, v98, v99
	ds_read_b64_tr_b16 v[96:97], v2 offset:43008
	ds_read_b64_tr_b16 v[98:99], v2 offset:43520
	v_add_f32_e32 v105, v54, v105
	v_add_f32_e32 v105, v55, v105
	v_add_f32_e32 v105, v56, v105
	v_add_f32_e32 v105, v57, v105
	v_cvt_pk_bf16_f32 v148, v52, v53
	v_cvt_pk_bf16_f32 v149, v54, v55
	s_waitcnt lgkmcnt(13)
	v_mfma_f32_32x32x16_bf16 v[68:83], v[106:109], v[136:139], v[68:83]
	ds_read_b64_tr_b16 v[52:53], v2 offset:47104
	ds_read_b64_tr_b16 v[54:55], v2 offset:47616
	s_waitcnt lgkmcnt(14)
	v_mfma_f32_32x32x16_bf16 v[36:51], v[164:167], v[136:139], v[36:51]
	v_add_f32_e32 v105, v58, v105
	v_add_f32_e32 v105, v59, v105
	v_add_f32_e32 v105, v60, v105
	v_add_f32_e32 v105, v61, v105
	v_cvt_pk_bf16_f32 v150, v56, v57
	v_cvt_pk_bf16_f32 v151, v58, v59
	ds_read_b64_tr_b16 v[56:57], v2 offset:44032
	ds_read_b64_tr_b16 v[58:59], v2 offset:44544
	v_add_f32_e32 v105, v62, v105
	v_add_f32_e32 v105, v63, v105
	v_add_f32_e32 v105, v64, v105
	v_add_f32_e32 v105, v65, v105
	v_cvt_pk_bf16_f32 v140, v60, v61
	v_cvt_pk_bf16_f32 v141, v62, v63
	s_waitcnt lgkmcnt(14)
	v_mfma_f32_32x32x16_bf16 v[68:83], v[110:113], v[132:135], v[68:83]
	ds_read_b64_tr_b16 v[60:61], v2 offset:48128
	ds_read_b64_tr_b16 v[62:63], v2 offset:48640
	v_mfma_f32_32x32x16_bf16 v[36:51], v[100:103], v[132:135], v[36:51]
	v_add_f32_e32 v2, v66, v105
	v_add_f32_e32 v2, v67, v2
	v_add_f32_e32 v2, 0, v2
	v_cvt_pk_bf16_f32 v142, v64, v65
	v_cvt_pk_bf16_f32 v143, v66, v67
	s_waitcnt lgkmcnt(14)
	v_mfma_f32_32x32x16_bf16 v[4:19], v[160:163], v[168:171], v[4:19]
	s_nop 1
	v_exp_f32_e32 v68, v68
	v_exp_f32_e32 v69, v69
	v_exp_f32_e32 v70, v70
	v_exp_f32_e32 v71, v71
	s_waitcnt lgkmcnt(12)
	v_mfma_f32_32x32x16_bf16 v[20:35], v[160:163], v[84:87], v[20:35]
	v_exp_f32_e32 v72, v72
	v_exp_f32_e32 v73, v73
	v_exp_f32_e32 v74, v74
	v_exp_f32_e32 v75, v75
	s_waitcnt lgkmcnt(10)
	v_mfma_f32_32x32x16_bf16 v[4:19], v[156:159], v[88:91], v[4:19]
	v_exp_f32_e32 v76, v76
	v_exp_f32_e32 v77, v77
	v_exp_f32_e32 v78, v78
	v_exp_f32_e32 v79, v79
	s_waitcnt lgkmcnt(8)
	v_mfma_f32_32x32x16_bf16 v[20:35], v[156:159], v[92:95], v[20:35]
	v_exp_f32_e32 v80, v80
	v_exp_f32_e32 v81, v81
	v_exp_f32_e32 v82, v82
	v_exp_f32_e32 v83, v83
	s_waitcnt lgkmcnt(6)
; #define SBAR() __builtin_amdgcn_sched_barrier(0)
;   #define RESC() do{ if(resc){ asm volatile("s_waitcnt lgkmcnt(0)":::"memory"); \
;       _Pragma("unroll") for(int d_=0;d_<2;++d_) _Pragma("unroll") for(int r=0;r<16;++r)o[d_][r]*=wsf[crow(r,hi)]; } }while(0)
;   #define PKW(P,B) cvtpk_s(P[B],P[B+1])
; __device__ __forceinline__ void pv(f32x16*o,int vb,bf16x8 pa0,bf16x8 pa1,bf16x8 pa2,bf16x8 pa3){
;   #pragma unroll
;   for(int d0=0;d0<2;++d0){s16x4 lo[4],hi[4];
;     #pragma unroll
;     for(int ks=0;ks<4;++ks){
;       asm volatile("ds_read_b64_tr_b16 %0,%1 offset:%c2":"=&v"(lo[ks]):"v"(vb),"i"(d0*4096+ks*1024):"memory");
;       asm volatile("ds_read_b64_tr_b16 %0,%1 offset:%c2":"=&v"(hi[ks]):"v"(vb),"i"(d0*4096+ks*1024+512):"memory");}
;     asm volatile("s_waitcnt lgkmcnt(0)":::"memory");SBAR();
;     ...
;     o[d0]=__builtin_amdgcn_mfma_f32_32x32x16_bf16(pa0,PK(0),o[d0],0,0,0);
;     o[d0]=__builtin_amdgcn_mfma_f32_32x32x16_bf16(pa1,PK(1),o[d0],0,0,0);
;     o[d0]=__builtin_amdgcn_mfma_f32_32x32x16_bf16(pa2,PK(2),o[d0],0,0,0);
;     o[d0]=__builtin_amdgcn_mfma_f32_32x32x16_bf16(pa3,PK(3),o[d0],0,0,0);
;     ...
;   }
; }
; template<int THRL,bool NOMAX> __device__ __forceinline__ void attn_unit(int b,int h,int qb,int t0,const bf16*Q,const bf16*__restrict__ KV,const bf16*__restrict__ GA,bf16*O,char*shm){
;     ...
;   STEP(pB0,pB1,pA0,pA1,NT-1,false,false,false); RESC();
;   { float sacc=pB0[0]+pB0[1]; _Pragma("unroll") for(int r=2;r<16;++r)sacc+=pB0[r]; _Pragma("unroll") for(int r=0;r<16;++r)sacc+=pB1[r]; l_reg+=sacc;
;     pw0=(u32x4){PKW(pB0,0),PKW(pB0,2),PKW(pB0,4),PKW(pB0,6)};pw1=(u32x4){PKW(pB0,8),PKW(pB0,10),PKW(pB0,12),PKW(pB0,14)};pw2=(u32x4){PKW(pB1,0),PKW(pB1,2),PKW(pB1,4),PKW(pB1,6)};pw3=(u32x4){PKW(pB1,8),PKW(pB1,10),PKW(pB1,12),PKW(pB1,14)};
;     SBAR(); pv(o,vb0+sl_cur,PAF(0),PAF(1),PAF(2),PAF(3)); }
;     ...
;   {auto rr=__builtin_amdgcn_permlane32_swap(__float_as_uint(l_reg),__float_as_uint(l_reg),false,false);l_reg=__uint_as_float(rr[0])+__uint_as_float(rr[1]);}
;   if(hi==0)wsf[32+r32]=l_reg;asm volatile("s_waitcnt lgkmcnt(0)":::"memory");
	v_mfma_f32_32x32x16_bf16 v[4:19], v[148:151], v[96:99], v[4:19]
	v_exp_f32_e32 v36, v36
	v_exp_f32_e32 v37, v37
	v_exp_f32_e32 v38, v38
	v_exp_f32_e32 v39, v39
	s_waitcnt lgkmcnt(4)
	v_mfma_f32_32x32x16_bf16 v[20:35], v[148:151], v[52:55], v[20:35]
	v_exp_f32_e32 v40, v40
	v_exp_f32_e32 v41, v41
	v_exp_f32_e32 v42, v42
	v_exp_f32_e32 v43, v43
	s_waitcnt lgkmcnt(2)
	v_mfma_f32_32x32x16_bf16 v[4:19], v[140:143], v[56:59], v[4:19]
	v_exp_f32_e32 v44, v44
	v_exp_f32_e32 v45, v45
	v_exp_f32_e32 v46, v46
	v_exp_f32_e32 v47, v47
	s_waitcnt lgkmcnt(0)
	v_mfma_f32_32x32x16_bf16 v[20:35], v[140:143], v[60:63], v[20:35]
	v_exp_f32_e32 v48, v48
	v_exp_f32_e32 v49, v49
	v_exp_f32_e32 v50, v50
	v_exp_f32_e32 v51, v51
	v_add_f32_e32 v52, v68, v69
	v_add_f32_e32 v52, v70, v52
	v_add_f32_e32 v52, v71, v52
	v_add_f32_e32 v52, v72, v52
	v_add_f32_e32 v52, v73, v52
	v_add_f32_e32 v52, v74, v52
	v_add_f32_e32 v52, v75, v52
	v_add_f32_e32 v52, v76, v52
	v_add_f32_e32 v52, v77, v52
	v_add_f32_e32 v52, v78, v52
	v_add_f32_e32 v52, v79, v52
	v_add_f32_e32 v52, v80, v52
	v_add_f32_e32 v52, v81, v52
	v_add_f32_e32 v52, v82, v52
	v_add_f32_e32 v52, v83, v52
	v_add_f32_e32 v52, v36, v52
	v_add_f32_e32 v52, v37, v52
	v_add_f32_e32 v52, v38, v52
	v_add_f32_e32 v52, v39, v52
	v_add_f32_e32 v52, v40, v52
	v_add_f32_e32 v52, v41, v52
	v_add_f32_e32 v52, v42, v52
	v_add_f32_e32 v52, v43, v52
	v_add_f32_e32 v52, v44, v52
	v_add_f32_e32 v52, v45, v52
	v_add_f32_e32 v52, v46, v52
	v_add_f32_e32 v52, v47, v52
	v_add_f32_e32 v52, v48, v52
	v_add_f32_e32 v52, v49, v52
	v_add_f32_e32 v52, v50, v52
	v_add_f32_e32 v52, v51, v52
	v_add_f32_e32 v2, v104, v2
	v_add_f32_e32 v2, v2, v52
	v_cvt_pk_bf16_f32 v36, v36, v37
	v_cvt_pk_bf16_f32 v52, v68, v69
	v_cvt_pk_bf16_f32 v53, v70, v71
	v_cvt_pk_bf16_f32 v54, v72, v73
	v_cvt_pk_bf16_f32 v55, v74, v75
	v_cvt_pk_bf16_f32 v56, v76, v77
	v_cvt_pk_bf16_f32 v57, v78, v79
	v_cvt_pk_bf16_f32 v58, v80, v81
	v_cvt_pk_bf16_f32 v59, v82, v83
	v_cvt_pk_bf16_f32 v37, v38, v39
	v_cvt_pk_bf16_f32 v38, v40, v41
	v_cvt_pk_bf16_f32 v39, v42, v43
	v_cvt_pk_bf16_f32 v40, v44, v45
	v_cvt_pk_bf16_f32 v41, v46, v47
	v_cvt_pk_bf16_f32 v42, v48, v49
	v_cvt_pk_bf16_f32 v43, v50, v51
	ds_read_b64_tr_b16 v[44:45],v190 offset:0
	ds_read_b64_tr_b16 v[46:47],v190 offset:512
	ds_read_b64_tr_b16 v[48:49],v190 offset:1024
	ds_read_b64_tr_b16 v[50:51],v190 offset:1536
	ds_read_b64_tr_b16 v[60:61],v190 offset:2048
	ds_read_b64_tr_b16 v[62:63],v190 offset:2560
	ds_read_b64_tr_b16 v[64:65],v190 offset:3072
	ds_read_b64_tr_b16 v[66:67],v190 offset:3584
	s_waitcnt lgkmcnt(0)
	s_nop 0
	v_mfma_f32_32x32x16_bf16 v[4:19], v[52:55], v[44:47], v[4:19]
	ds_read_b64_tr_b16 v[44:45],v190 offset:4096
	ds_read_b64_tr_b16 v[46:47],v190 offset:4608
	v_mfma_f32_32x32x16_bf16 v[4:19], v[56:59], v[48:51], v[4:19]
	ds_read_b64_tr_b16 v[48:49],v190 offset:5120
	ds_read_b64_tr_b16 v[50:51],v190 offset:5632
	v_mfma_f32_32x32x16_bf16 v[4:19], v[36:39], v[60:63], v[4:19]
	ds_read_b64_tr_b16 v[60:61],v190 offset:6144
	ds_read_b64_tr_b16 v[62:63],v190 offset:6656
	v_mfma_f32_32x32x16_bf16 v[4:19], v[40:43], v[64:67], v[4:19]
	ds_read_b64_tr_b16 v[64:65],v190 offset:7168
	ds_read_b64_tr_b16 v[66:67],v190 offset:7680
	s_waitcnt lgkmcnt(0)
	v_mfma_f32_32x32x16_bf16 v[20:35], v[52:55], v[44:47], v[20:35]
	v_cmp_gt_u32_e32 vcc, 32, v184
	v_mfma_f32_32x32x16_bf16 v[20:35], v[56:59], v[48:51], v[20:35]
	v_mfma_f32_32x32x16_bf16 v[20:35], v[36:39], v[60:63], v[20:35]
	v_mov_b32_e32 v36, v2
	s_nop 1
	v_permlane32_swap_b32_e32 v2, v36
	v_mfma_f32_32x32x16_bf16 v[20:35], v[40:43], v[64:67], v[20:35]
	s_and_saveexec_b64 s[8:9], vcc
	s_cbranch_execz .LBB0_470
	v_lshl_add_u32 v37, v185, 2, s12
	v_add_f32_e32 v2, v2, v36
	ds_write_b32 v37, v2 offset:49280
	s_branch .LBB0_470
